# B2 row loop rewritten by hand: row-invariant gains/conv weights hoisted, 3 rows of loads in flight with counted vmcnt, DPP butterfly
# speedup vs baseline: 1.0347x; 1.0140x over previous
; __device__ __forceinline__ void phase_B2(CArgs& a, int l, unsigned char* lds, const int tid, const int bx, const int G) {
;     ...
;     const float lam = ((const float*)(ws + WS_LAM))[l];
;     const float post = 1.f - (0.8f - 0.6f * expf(-0.3f * (float)l));
;     const bf16_t* OR = (const bf16_t*)(ws + WS_XB); bf16_t* OC = (bf16_t*)(R + R_OCAT);
;     const bf16_t* SB = (const bf16_t*)(R + R_SCB); const bf16_t* SC = (const bf16_t*)(R + R_SCC); const bf16_t* SX = (const bf16_t*)(R + R_SCX);
; #pragma unroll 4
;     for (int row = gw; row < MT; row += NGW) {
;         {
;             const int h = lane >> 4, e0 = (lane & 15) * 8;
;             const u32x4 w0 = *(const u32x4*)(OR + (size_t)row * 1024 + h * 256 + e0), w1 = *(const u32x4*)(OR + (size_t)row * 1024 + h * 256 + 128 + e0);
;             float v[8] = {bflo(w0.x) - lam * bflo(w1.x), bfhi(w0.x) - lam * bfhi(w1.x), bflo(w0.y) - lam * bflo(w1.y), bfhi(w0.y) - lam * bfhi(w1.y),
;                           bflo(w0.z) - lam * bflo(w1.z), bfhi(w0.z) - lam * bfhi(w1.z), bflo(w0.w) - lam * bflo(w1.w), bfhi(w0.w) - lam * bfhi(w1.w)};
;             float s = 0.f;
; #pragma unroll
;             for (int i = 0; i < 8; ++i) s += v[i] * v[i];
;             s += __shfl_xor(s, 1); s += __shfl_xor(s, 2); s += __shfl_xor(s, 4); s += __shfl_xor(s, 8);
;             const float r = rsqrtf(s * (1.f / 128.f) + EPS) * post; const float* g = a.in[I_SUBLN] + l * 128 + e0;
;             u32x4 o; o.x = cvt_pk_bf16(v[0] * r * g[0], v[1] * r * g[1]); o.y = cvt_pk_bf16(v[2] * r * g[2], v[3] * r * g[3]);
;             o.z = cvt_pk_bf16(v[4] * r * g[4], v[5] * r * g[5]); o.w = cvt_pk_bf16(v[6] * r * g[6], v[7] * r * g[7]);
;             *(u32x4*)(OC + (size_t)row * 1024 + h * 128 + e0) = o;
;         }
;         if (lane < 32) {
;             const int ch = lane * 8, pos = row & (SEQ - 1);
;             const float* cw = a.in[I_SCW] + l * 3 * 256 + ch; const float* cb = a.in[I_SCB] + l * 256 + ch;
;             float y[8];
; #pragma unroll
;             for (int i = 0; i < 8; ++i) y[i] = cb[i];
; #pragma unroll
;             for (int k = 0; k < 3; ++k) { const int dt = 2 - k; if (pos >= dt) {
;                 const u32x4 cv = *(const u32x4*)(SC + (size_t)(row - dt) * 256 + ch), xv = *(const u32x4*)(SX + (size_t)(row - dt) * 256 + ch); const float* w = cw + k * 256;
.LBB0_155:
	s_lshl_b32 s11, s11, 3
	v_add_u32_e32 v2, s11, v66
	s_mov_b32 s4, 0x8000
	v_cmp_gt_i32_e32 vcc, s4, v2
	s_and_saveexec_b64 s[6:7], vcc
	s_cbranch_execz .LBB0_164
	s_ashr_i32 s19, s18, 31
	s_lshl_b64 s[4:5], s[18:19], 2
	s_waitcnt lgkmcnt(0)
	s_add_u32 s4, s8, s4
	s_addc_u32 s5, s9, s5
	global_load_dword v10, v185, s[4:5]
	v_and_b32_e32 v0, 64, v187
	v_xor_b32_e32 v11, 1, v187
	v_add_u32_e32 v16, 64, v0
	v_xor_b32_e32 v13, 2, v187
	v_cmp_lt_i32_e32 vcc, v11, v16
	v_cvt_f32_i32_e32 v8, s18
	v_xor_b32_e32 v14, 4, v187
	v_cndmask_b32_e32 v11, v187, v11, vcc
	v_cmp_lt_i32_e32 vcc, v13, v16
	v_lshlrev_b32_e32 v4, 4, v75
	v_xor_b32_e32 v15, 8, v187
	v_mov_b32_e32 v5, v1
	v_cndmask_b32_e32 v13, v187, v13, vcc
	v_cmp_lt_i32_e32 vcc, v14, v16
	s_load_dwordx2 s[48:49], s[22:23], 0x40
	s_load_dwordx4 s[12:15], s[22:23], 0x50
	s_mov_b64 s[22:23], 0x11600000
	v_and_b32_e32 v30, 0x300, v4
	v_lshl_add_u64 v[4:5], s[8:9], 0, v[4:5]
	v_cndmask_b32_e32 v18, v187, v14, vcc
	v_cmp_lt_i32_e32 vcc, v15, v16
	s_mov_b64 s[26:27], 0x12600000
	v_add3_u32 v12, v66, s11, -1
	v_cndmask_b32_e32 v19, v187, v15, vcc
	v_lshl_add_u64 v[14:15], v[4:5], 0, s[22:23]
	s_lshl_b32 s22, s10, 3
	s_lshl_b32 s10, s18, 7
	v_lshl_add_u64 v[16:17], v[4:5], 0, s[26:27]
	v_mul_f32_e32 v4, 0xbe99999a, v8
	s_ashr_i32 s11, s10, 31
	v_mul_f32_e32 v5, 0x3fb8aa3b, v4
	s_lshl_b64 s[10:11], s[10:11], 2
	s_mov_b32 s19, 0x3fb8aa3b
	v_lshlrev_b32_e32 v26, 5, v94
	s_mul_i32 s50, s18, 0x300
	v_lshlrev_b32_e32 v32, 2, v11
	v_fma_f32 v8, v4, s19, -v5
	v_rndne_f32_e32 v11, v5
	s_waitcnt lgkmcnt(0)
	s_add_u32 s10, s48, s10
	v_and_b32_e32 v0, 0x1e0, v26
	v_fmac_f32_e32 v8, 0x32a5705f, v4
	v_sub_f32_e32 v5, v5, v11
	s_addc_u32 s11, s49, s11
	s_ashr_i32 s51, s50, 31
	v_lshlrev_b32_e32 v34, 2, v18
	v_lshlrev_b32_e32 v35, 2, v19
	v_add_f32_e32 v5, v5, v8
	v_lshl_add_u64 v[18:19], s[10:11], 0, v[0:1]
	s_lshl_b64 s[10:11], s[50:51], 2
	v_cvt_i32_f32_e32 v11, v11
	v_exp_f32_e32 v5, v5
	s_add_u32 s10, s12, s10
	s_addc_u32 s11, s13, s11
	s_lshl_b32 s12, s18, 8
	v_lshlrev_b32_e32 v0, 5, v75
	s_ashr_i32 s13, s12, 31
	v_lshl_add_u64 v[20:21], s[10:11], 0, v[0:1]
	s_lshl_b64 s[10:11], s[12:13], 2
	s_mov_b32 s12, 0xc2ce8ed0
	v_ldexp_f32 v5, v5, v11
	v_cmp_ngt_f32_e32 vcc, s12, v4
	s_mov_b32 s12, 0x42b17218
	s_add_u32 s10, s14, s10
	v_cndmask_b32_e32 v5, 0, v5, vcc
	v_cmp_nlt_f32_e32 vcc, s12, v4
	v_mov_b32_e32 v9, 0xbf4ccccd
	v_ashrrev_i32_e32 v3, 31, v2
	s_addc_u32 s11, s15, s11
	v_cndmask_b32_e32 v4, v254, v5, vcc
	v_lshlrev_b64 v[6:7], 9, v[2:3]
	v_lshl_add_u64 v[22:23], s[10:11], 0, v[0:1]
	v_and_b32_e32 v0, 0x3f0, v73
	v_fmamk_f32 v4, v4, 0x3f19999a, v9
	v_lshlrev_b64 v[2:3], 11, v[2:3]
	v_lshl_add_u64 v[24:25], v[6:7], 0, v[0:1]
	v_add_f32_e32 v36, 1.0, v4
	v_and_b32_e32 v4, 0x600, v26
	v_and_b32_e32 v6, 0xf0, v73
	v_or3_b32 v26, v2, v4, v6
	v_or_b32_e32 v4, v2, v0
	v_mov_b32_e32 v5, v3
	s_mov_b64 s[10:11], 0x6600600
	s_ashr_i32 s23, s22, 31
	v_lshl_add_u64 v[28:29], v[4:5], 0, s[10:11]
	v_or3_b32 v2, v2, v30, v6
	s_mov_b64 s[10:11], 0x6600000
	v_cmp_gt_u32_e64 s[4:5], 32, v75
	v_lshlrev_b32_e32 v33, 2, v13
	s_lshl_b64 s[12:13], s[22:23], 9
	s_waitcnt vmcnt(0)
	v_mov_b32_e32 v11, v10
	v_mov_b32_e32 v27, v3
	s_lshl_b64 s[14:15], s[22:23], 11
	v_lshl_add_u64 v[30:31], v[2:3], 0, s[10:11]
	s_branch .Lrw_start
.Lrw_start:
	s_mov_b64 exec, -1
	s_add_u32 s10, s8, 0x10600000
	s_addc_u32 s11, s9, 0
	s_add_u32 s12, s8, 0x11600000
	s_addc_u32 s13, s9, 0
	s_add_u32 s14, s8, 0x12600000
	s_addc_u32 s15, s9, 0
	s_add_u32 s18, s8, 0x2600000
	s_addc_u32 s19, s9, 0
	s_lshl_b32 s48, s2, 3
	s_add_i32 s48, s48, s3
	s_lshl_b32 s49, s37, 3
	s_lshl_b32 s50, s49, 9
	s_lshl_b32 s51, s49, 11
	s_mov_b32 s26, 0xffff0000
	s_mov_b32 s27, 0x8000
	global_load_dwordx4 v[96:99], v[18:19], off
	global_load_dwordx4 v[100:103], v[18:19], off offset:16
	s_mov_b64 exec, s[4:5]
	global_load_dwordx4 v[104:107], v[22:23], off
	global_load_dwordx4 v[108:111], v[22:23], off offset:16
	global_load_dwordx4 v[112:115], v[20:21], off offset:0
	global_load_dwordx4 v[116:119], v[20:21], off offset:16
	global_load_dwordx4 v[120:123], v[20:21], off offset:1024
	global_load_dwordx4 v[124:127], v[20:21], off offset:1040
	global_load_dwordx4 v[128:131], v[20:21], off offset:2048
	global_load_dwordx4 v[132:135], v[20:21], off offset:2064
	s_mov_b64 exec, s[4:5]
	global_load_dwordx4 v[206:209], v24, s[12:13] offset:-1024
	global_load_dwordx4 v[210:213], v24, s[14:15] offset:-1024
	global_load_dwordx4 v[214:217], v24, s[12:13] offset:-512
	global_load_dwordx4 v[218:221], v24, s[14:15] offset:-512
	global_load_dwordx4 v[222:225], v24, s[12:13]
	global_load_dwordx4 v[226:229], v24, s[14:15]
	global_load_dwordx4 v[230:233], v24, s[10:11]
	s_mov_b64 exec, -1
	global_load_dwordx4 v[198:201], v26, s[18:19]
	global_load_dwordx4 v[202:205], v26, s[18:19] offset:256
	v_add_u32_e32 v24, s50, v24
	v_add_u32_e32 v26, s51, v26
	s_mov_b64 exec, s[4:5]
	global_load_dwordx4 v[164:167], v24, s[12:13] offset:-1024
	global_load_dwordx4 v[168:171], v24, s[14:15] offset:-1024
	global_load_dwordx4 v[172:175], v24, s[12:13] offset:-512
	global_load_dwordx4 v[176:179], v24, s[14:15] offset:-512
	global_load_dwordx4 v[180:183], v24, s[12:13]
	global_load_dwordx4 v[234:237], v24, s[14:15]
	global_load_dwordx4 v[238:241], v24, s[10:11]
	s_mov_b64 exec, -1
	global_load_dwordx4 v[156:159], v26, s[18:19]
	global_load_dwordx4 v[160:163], v26, s[18:19] offset:256
	v_add_u32_e32 v24, s50, v24
	v_add_u32_e32 v26, s51, v26
	s_mov_b64 exec, s[4:5]
	global_load_dwordx4 v[48:51], v24, s[12:13] offset:-1024
	global_load_dwordx4 v[52:55], v24, s[14:15] offset:-1024
	global_load_dwordx4 v[56:59], v24, s[12:13] offset:-512
	global_load_dwordx4 v[60:63], v24, s[14:15] offset:-512
	global_load_dwordx4 v[76:79], v24, s[12:13]
	global_load_dwordx4 v[80:83], v24, s[14:15]
	global_load_dwordx4 v[84:87], v24, s[10:11]
	s_mov_b64 exec, -1
	global_load_dwordx4 v[40:43], v26, s[18:19]
	global_load_dwordx4 v[44:47], v26, s[18:19] offset:256
	v_add_u32_e32 v24, s50, v24
	v_add_u32_e32 v26, s51, v26
	s_waitcnt vmcnt(9)
; __device__ __forceinline__ float bflo(unsigned w) { return __uint_as_float(w << 16); }
; __device__ __forceinline__ void phase_B2(CArgs& a, int l, unsigned char* lds, const int tid, const int bx, const int G) {
;     ...
;         {
;             const int h = lane >> 4, e0 = (lane & 15) * 8;
;             const u32x4 w0 = *(const u32x4*)(OR + (size_t)row * 1024 + h * 256 + e0), w1 = *(const u32x4*)(OR + (size_t)row * 1024 + h * 256 + 128 + e0);
;             float v[8] = {bflo(w0.x) - lam * bflo(w1.x), bfhi(w0.x) - lam * bfhi(w1.x), bflo(w0.y) - lam * bflo(w1.y), bfhi(w0.y) - lam * bfhi(w1.y),
;                           bflo(w0.z) - lam * bflo(w1.z), bfhi(w0.z) - lam * bfhi(w1.z), bflo(w0.w) - lam * bflo(w1.w), bfhi(w0.w) - lam * bfhi(w1.w)};
;             float s = 0.f;
; #pragma unroll
;             for (int i = 0; i < 8; ++i) s += v[i] * v[i];
;             s += __shfl_xor(s, 1); s += __shfl_xor(s, 2); s += __shfl_xor(s, 4); s += __shfl_xor(s, 8);
;             const float r = rsqrtf(s * (1.f / 128.f) + EPS) * post; const float* g = a.in[I_SUBLN] + l * 128 + e0;
;             u32x4 o; o.x = cvt_pk_bf16(v[0] * r * g[0], v[1] * r * g[1]); o.y = cvt_pk_bf16(v[2] * r * g[2], v[3] * r * g[3]);
;             o.z = cvt_pk_bf16(v[4] * r * g[4], v[5] * r * g[5]); o.w = cvt_pk_bf16(v[6] * r * g[6], v[7] * r * g[7]);
;             *(u32x4*)(OC + (size_t)row * 1024 + h * 128 + e0) = o;
;         }
;         if (lane < 32) {
;             const int ch = lane * 8, pos = row & (SEQ - 1);
;             const float* cw = a.in[I_SCW] + l * 3 * 256 + ch; const float* cb = a.in[I_SCB] + l * 256 + ch;
;             float y[8];
; #pragma unroll
;             for (int i = 0; i < 8; ++i) y[i] = cb[i];
; #pragma unroll
;             for (int k = 0; k < 3; ++k) { const int dt = 2 - k; if (pos >= dt) {
;                 const u32x4 cv = *(const u32x4*)(SC + (size_t)(row - dt) * 256 + ch), xv = *(const u32x4*)(SX + (size_t)(row - dt) * 256 + ch); const float* w = cw + k * 256;
;                 y[0] += w[0] * bflo(cv.x) * bflo(xv.x); y[1] += w[1] * bfhi(cv.x) * bfhi(xv.x); y[2] += w[2] * bflo(cv.y) * bflo(xv.y); y[3] += w[3] * bfhi(cv.y) * bfhi(xv.y);
;                 y[4] += w[4] * bflo(cv.z) * bflo(xv.z); y[5] += w[5] * bfhi(cv.z) * bfhi(xv.z); y[6] += w[6] * bflo(cv.w) * bflo(xv.w); y[7] += w[7] * bfhi(cv.w) * bfhi(xv.w); } }
.Lrw_body0:
	s_cmp_ge_u32 s48, s27
	s_cbranch_scc1 .Lrw_exit
	s_waitcnt vmcnt(22)
	v_lshlrev_b32_e32 v136, 16, v198
	v_and_b32_e32 v137, s26, v198
	v_lshlrev_b32_e32 v138, 16, v199
	v_and_b32_e32 v139, s26, v199
	v_lshlrev_b32_e32 v140, 16, v200
	v_and_b32_e32 v141, s26, v200
	v_lshlrev_b32_e32 v142, 16, v201
	v_and_b32_e32 v143, s26, v201
	v_lshlrev_b32_e32 v242, 16, v202
	v_and_b32_e32 v243, s26, v202
	v_lshlrev_b32_e32 v244, 16, v203
	v_and_b32_e32 v245, s26, v203
	v_lshlrev_b32_e32 v246, 16, v204
	v_and_b32_e32 v247, s26, v204
	v_lshlrev_b32_e32 v248, 16, v205
	v_and_b32_e32 v249, s26, v205
	v_pk_fma_f32 v[136:137], v[10:11], v[242:243], v[136:137] neg_lo:[1,0,0] neg_hi:[1,0,0]
	v_pk_fma_f32 v[138:139], v[10:11], v[244:245], v[138:139] neg_lo:[1,0,0] neg_hi:[1,0,0]
	v_pk_fma_f32 v[140:141], v[10:11], v[246:247], v[140:141] neg_lo:[1,0,0] neg_hi:[1,0,0]
	v_pk_fma_f32 v[142:143], v[10:11], v[248:249], v[142:143] neg_lo:[1,0,0] neg_hi:[1,0,0]
	v_mul_f32_e32 v0, v137, v137
	v_pk_mul_f32 v[244:245], v[138:139], v[138:139]
	v_pk_mul_f32 v[246:247], v[140:141], v[140:141]
	v_pk_mul_f32 v[248:249], v[142:143], v[142:143]
	v_fmac_f32_e32 v0, v136, v136
	v_add_f32_e32 v0, v244, v0
	v_add_f32_e32 v0, v245, v0
	v_add_f32_e32 v0, v246, v0
	v_add_f32_e32 v0, v247, v0
	v_add_f32_e32 v0, v248, v0
	v_add_f32_e32 v0, v249, v0
	s_nop 1
	v_add_f32_dpp v0, v0, v0 quad_perm:[1,0,3,2] row_mask:0xf bank_mask:0xf
	s_nop 1
	v_add_f32_dpp v0, v0, v0 quad_perm:[2,3,0,1] row_mask:0xf bank_mask:0xf
	s_nop 1
	v_add_f32_dpp v0, v0, v0 row_half_mirror row_mask:0xf bank_mask:0xf
	s_nop 1
	v_add_f32_dpp v0, v0, v0 row_mirror row_mask:0xf bank_mask:0xf
	s_nop 0
	v_fmamk_f32 v0, v0, 0x3c000000, v184
	v_mul_f32_e32 v13, 0x4b800000, v0
	v_cmp_gt_f32_e32 vcc, s74, v0
	s_nop 1
	v_cndmask_b32_e32 v0, v0, v13, vcc
	v_rsq_f32_e32 v0, v0
	s_nop 0
	v_mul_f32_e32 v13, 0x45800000, v0
	v_cndmask_b32_e32 v0, v0, v13, vcc
	v_mul_f32_e32 v0, v36, v0
	v_pk_mul_f32 v[242:243], v[136:137], v[0:1] op_sel_hi:[1,0]
	v_pk_mul_f32 v[244:245], v[138:139], v[0:1] op_sel_hi:[1,0]
	v_pk_mul_f32 v[246:247], v[140:141], v[0:1] op_sel_hi:[1,0]
	v_pk_mul_f32 v[248:249], v[142:143], v[0:1] op_sel_hi:[1,0]
	v_pk_mul_f32 v[242:243], v[96:97], v[242:243]
	v_pk_mul_f32 v[244:245], v[98:99], v[244:245]
	v_pk_mul_f32 v[246:247], v[100:101], v[246:247]
	v_pk_mul_f32 v[248:249], v[102:103], v[248:249]
	v_cvt_pk_bf16_f32 v250, v242, v243
	v_cvt_pk_bf16_f32 v251, v244, v245
	v_cvt_pk_bf16_f32 v252, v246, v247
	v_cvt_pk_bf16_f32 v253, v248, v249
	global_store_dwordx4 v30, v[250:253], s[8:9]
	s_mov_b64 exec, s[4:5]
	s_and_b32 s22, s48, 0xfff
	v_mov_b32_e32 v2, v104
	v_mov_b32_e32 v3, v105
	v_mov_b32_e32 v4, v106
	v_mov_b32_e32 v5, v107
	v_mov_b32_e32 v6, v108
	v_mov_b32_e32 v7, v109
	v_mov_b32_e32 v8, v110
	v_mov_b32_e32 v9, v111
	s_cmp_lt_u32 s22, 2
	s_cbranch_scc1 .Lrw_t1_0
	v_lshlrev_b32_e32 v136, 16, v206
	v_and_b32_e32 v137, s26, v206
	v_lshlrev_b32_e32 v138, 16, v207
	v_and_b32_e32 v139, s26, v207
	v_lshlrev_b32_e32 v140, 16, v208
	v_and_b32_e32 v141, s26, v208
	v_lshlrev_b32_e32 v142, 16, v209
	v_and_b32_e32 v143, s26, v209
	v_lshlrev_b32_e32 v242, 16, v210
	v_and_b32_e32 v243, s26, v210
	v_lshlrev_b32_e32 v244, 16, v211
	v_and_b32_e32 v245, s26, v211
	v_lshlrev_b32_e32 v246, 16, v212
	v_and_b32_e32 v247, s26, v212
	v_lshlrev_b32_e32 v248, 16, v213
	v_and_b32_e32 v249, s26, v213
	v_pk_mul_f32 v[136:137], v[112:113], v[136:137]
	v_pk_mul_f32 v[138:139], v[114:115], v[138:139]
	v_pk_mul_f32 v[140:141], v[116:117], v[140:141]
	v_pk_mul_f32 v[142:143], v[118:119], v[142:143]
	v_pk_fma_f32 v[2:3], v[136:137], v[242:243], v[2:3]
	v_pk_fma_f32 v[4:5], v[138:139], v[244:245], v[4:5]
	v_pk_fma_f32 v[6:7], v[140:141], v[246:247], v[6:7]
	v_pk_fma_f32 v[8:9], v[142:143], v[248:249], v[8:9]
.Lrw_t1_0:
	s_cmp_lt_u32 s22, 1
	s_cbranch_scc1 .Lrw_t0_0
	v_lshlrev_b32_e32 v136, 16, v214
	v_and_b32_e32 v137, s26, v214
	v_lshlrev_b32_e32 v138, 16, v215
	v_and_b32_e32 v139, s26, v215
	v_lshlrev_b32_e32 v140, 16, v216
	v_and_b32_e32 v141, s26, v216
	v_lshlrev_b32_e32 v142, 16, v217
	v_and_b32_e32 v143, s26, v217
	v_lshlrev_b32_e32 v242, 16, v218
	v_and_b32_e32 v243, s26, v218
	v_lshlrev_b32_e32 v244, 16, v219
	v_and_b32_e32 v245, s26, v219
	v_lshlrev_b32_e32 v246, 16, v220
	v_and_b32_e32 v247, s26, v220
	v_lshlrev_b32_e32 v248, 16, v221
	v_and_b32_e32 v249, s26, v221
	v_pk_mul_f32 v[136:137], v[120:121], v[136:137]
	v_pk_mul_f32 v[138:139], v[122:123], v[138:139]
	v_pk_mul_f32 v[140:141], v[124:125], v[140:141]
	v_pk_mul_f32 v[142:143], v[126:127], v[142:143]
	v_pk_fma_f32 v[2:3], v[136:137], v[242:243], v[2:3]
	v_pk_fma_f32 v[4:5], v[138:139], v[244:245], v[4:5]
	v_pk_fma_f32 v[6:7], v[140:141], v[246:247], v[6:7]
	v_pk_fma_f32 v[8:9], v[142:143], v[248:249], v[8:9]
; __device__ __forceinline__ void phase_B2(CArgs& a, int l, unsigned char* lds, const int tid, const int bx, const int G) {
;     ...
;         {
;             const int h = lane >> 4, e0 = (lane & 15) * 8;
;             const u32x4 w0 = *(const u32x4*)(OR + (size_t)row * 1024 + h * 256 + e0), w1 = *(const u32x4*)(OR + (size_t)row * 1024 + h * 256 + 128 + e0);
;             float v[8] = {bflo(w0.x) - lam * bflo(w1.x), bfhi(w0.x) - lam * bfhi(w1.x), bflo(w0.y) - lam * bflo(w1.y), bfhi(w0.y) - lam * bfhi(w1.y),
;                           bflo(w0.z) - lam * bflo(w1.z), bfhi(w0.z) - lam * bfhi(w1.z), bflo(w0.w) - lam * bflo(w1.w), bfhi(w0.w) - lam * bfhi(w1.w)};
;             float s = 0.f;
; #pragma unroll
;             for (int i = 0; i < 8; ++i) s += v[i] * v[i];
;             s += __shfl_xor(s, 1); s += __shfl_xor(s, 2); s += __shfl_xor(s, 4); s += __shfl_xor(s, 8);
;             const float r = rsqrtf(s * (1.f / 128.f) + EPS) * post; const float* g = a.in[I_SUBLN] + l * 128 + e0;
;     ...
;         if (lane < 32) {
;             const int ch = lane * 8, pos = row & (SEQ - 1);
;             const float* cw = a.in[I_SCW] + l * 3 * 256 + ch; const float* cb = a.in[I_SCB] + l * 256 + ch;
;             float y[8];
; #pragma unroll
;             for (int i = 0; i < 8; ++i) y[i] = cb[i];
; #pragma unroll
;             for (int k = 0; k < 3; ++k) { const int dt = 2 - k; if (pos >= dt) {
;                 const u32x4 cv = *(const u32x4*)(SC + (size_t)(row - dt) * 256 + ch), xv = *(const u32x4*)(SX + (size_t)(row - dt) * 256 + ch); const float* w = cw + k * 256;
;                 y[0] += w[0] * bflo(cv.x) * bflo(xv.x); y[1] += w[1] * bfhi(cv.x) * bfhi(xv.x); y[2] += w[2] * bflo(cv.y) * bflo(xv.y); y[3] += w[3] * bfhi(cv.y) * bfhi(xv.y);
;                 y[4] += w[4] * bflo(cv.z) * bflo(xv.z); y[5] += w[5] * bfhi(cv.z) * bfhi(xv.z); y[6] += w[6] * bflo(cv.w) * bflo(xv.w); y[7] += w[7] * bfhi(cv.w) * bfhi(xv.w); } }
;             const u32x4 bv = *(const u32x4*)(SB + (size_t)row * 256 + ch);
;             u32x4 o; o.x = cvt_pk_bf16(y[0] * bflo(bv.x), y[1] * bfhi(bv.x)); o.y = cvt_pk_bf16(y[2] * bflo(bv.y), y[3] * bfhi(bv.y));
;             o.z = cvt_pk_bf16(y[4] * bflo(bv.z), y[5] * bfhi(bv.z)); o.w = cvt_pk_bf16(y[6] * bflo(bv.w), y[7] * bfhi(bv.w));
;             *(u32x4*)(OC + (size_t)row * 1024 + 768 + ch) = o;
.Lrw_t0_0:
	v_lshlrev_b32_e32 v136, 16, v222
	v_and_b32_e32 v137, s26, v222
	v_lshlrev_b32_e32 v138, 16, v223
	v_and_b32_e32 v139, s26, v223
	v_lshlrev_b32_e32 v140, 16, v224
	v_and_b32_e32 v141, s26, v224
	v_lshlrev_b32_e32 v142, 16, v225
	v_and_b32_e32 v143, s26, v225
	v_lshlrev_b32_e32 v242, 16, v226
	v_and_b32_e32 v243, s26, v226
	v_lshlrev_b32_e32 v244, 16, v227
	v_and_b32_e32 v245, s26, v227
	v_lshlrev_b32_e32 v246, 16, v228
	v_and_b32_e32 v247, s26, v228
	v_lshlrev_b32_e32 v248, 16, v229
	v_and_b32_e32 v249, s26, v229
	v_pk_mul_f32 v[136:137], v[128:129], v[136:137]
	v_pk_mul_f32 v[138:139], v[130:131], v[138:139]
	v_pk_mul_f32 v[140:141], v[132:133], v[140:141]
	v_pk_mul_f32 v[142:143], v[134:135], v[142:143]
	v_pk_fma_f32 v[2:3], v[136:137], v[242:243], v[2:3]
	v_pk_fma_f32 v[4:5], v[138:139], v[244:245], v[4:5]
	v_pk_fma_f32 v[6:7], v[140:141], v[246:247], v[6:7]
	v_pk_fma_f32 v[8:9], v[142:143], v[248:249], v[8:9]
	v_lshlrev_b32_e32 v136, 16, v230
	v_and_b32_e32 v137, s26, v230
	v_lshlrev_b32_e32 v138, 16, v231
	v_and_b32_e32 v139, s26, v231
	v_lshlrev_b32_e32 v140, 16, v232
	v_and_b32_e32 v141, s26, v232
	v_lshlrev_b32_e32 v142, 16, v233
	v_and_b32_e32 v143, s26, v233
	v_pk_mul_f32 v[2:3], v[2:3], v[136:137]
	v_pk_mul_f32 v[4:5], v[4:5], v[138:139]
	v_pk_mul_f32 v[6:7], v[6:7], v[140:141]
	v_pk_mul_f32 v[8:9], v[8:9], v[142:143]
	v_cvt_pk_bf16_f32 v88, v2, v3
	v_cvt_pk_bf16_f32 v89, v4, v5
	v_cvt_pk_bf16_f32 v90, v6, v7
	v_cvt_pk_bf16_f32 v91, v8, v9
	global_store_dwordx4 v28, v[88:91], s[8:9]
	s_mov_b64 exec, s[4:5]
	global_load_dwordx4 v[206:209], v24, s[12:13] offset:-1024
	global_load_dwordx4 v[210:213], v24, s[14:15] offset:-1024
	global_load_dwordx4 v[214:217], v24, s[12:13] offset:-512
	global_load_dwordx4 v[218:221], v24, s[14:15] offset:-512
	global_load_dwordx4 v[222:225], v24, s[12:13]
	global_load_dwordx4 v[226:229], v24, s[14:15]
	global_load_dwordx4 v[230:233], v24, s[10:11]
	s_mov_b64 exec, -1
	global_load_dwordx4 v[198:201], v26, s[18:19]
	global_load_dwordx4 v[202:205], v26, s[18:19] offset:256
	v_add_u32_e32 v24, s50, v24
	v_add_u32_e32 v26, s51, v26
	v_add_u32_e32 v30, s51, v30
	v_add_u32_e32 v28, s51, v28
	s_add_i32 s48, s48, s49
.Lrw_body1:
	s_cmp_ge_u32 s48, s27
	s_cbranch_scc1 .Lrw_exit
	s_waitcnt vmcnt(22)
	v_lshlrev_b32_e32 v136, 16, v156
	v_and_b32_e32 v137, s26, v156
	v_lshlrev_b32_e32 v138, 16, v157
	v_and_b32_e32 v139, s26, v157
	v_lshlrev_b32_e32 v140, 16, v158
	v_and_b32_e32 v141, s26, v158
	v_lshlrev_b32_e32 v142, 16, v159
	v_and_b32_e32 v143, s26, v159
	v_lshlrev_b32_e32 v242, 16, v160
	v_and_b32_e32 v243, s26, v160
	v_lshlrev_b32_e32 v244, 16, v161
	v_and_b32_e32 v245, s26, v161
	v_lshlrev_b32_e32 v246, 16, v162
	v_and_b32_e32 v247, s26, v162
	v_lshlrev_b32_e32 v248, 16, v163
	v_and_b32_e32 v249, s26, v163
	v_pk_fma_f32 v[136:137], v[10:11], v[242:243], v[136:137] neg_lo:[1,0,0] neg_hi:[1,0,0]
	v_pk_fma_f32 v[138:139], v[10:11], v[244:245], v[138:139] neg_lo:[1,0,0] neg_hi:[1,0,0]
	v_pk_fma_f32 v[140:141], v[10:11], v[246:247], v[140:141] neg_lo:[1,0,0] neg_hi:[1,0,0]
	v_pk_fma_f32 v[142:143], v[10:11], v[248:249], v[142:143] neg_lo:[1,0,0] neg_hi:[1,0,0]
	v_mul_f32_e32 v0, v137, v137
	v_pk_mul_f32 v[244:245], v[138:139], v[138:139]
	v_pk_mul_f32 v[246:247], v[140:141], v[140:141]
	v_pk_mul_f32 v[248:249], v[142:143], v[142:143]
	v_fmac_f32_e32 v0, v136, v136
	v_add_f32_e32 v0, v244, v0
	v_add_f32_e32 v0, v245, v0
	v_add_f32_e32 v0, v246, v0
	v_add_f32_e32 v0, v247, v0
	v_add_f32_e32 v0, v248, v0
	v_add_f32_e32 v0, v249, v0
	s_nop 1
	v_add_f32_dpp v0, v0, v0 quad_perm:[1,0,3,2] row_mask:0xf bank_mask:0xf
	s_nop 1
	v_add_f32_dpp v0, v0, v0 quad_perm:[2,3,0,1] row_mask:0xf bank_mask:0xf
	s_nop 1
	v_add_f32_dpp v0, v0, v0 row_half_mirror row_mask:0xf bank_mask:0xf
	s_nop 1
	v_add_f32_dpp v0, v0, v0 row_mirror row_mask:0xf bank_mask:0xf
	s_nop 0
	v_fmamk_f32 v0, v0, 0x3c000000, v184
	v_mul_f32_e32 v13, 0x4b800000, v0
	v_cmp_gt_f32_e32 vcc, s74, v0
	s_nop 1
	v_cndmask_b32_e32 v0, v0, v13, vcc
	v_rsq_f32_e32 v0, v0
	s_nop 0
	v_mul_f32_e32 v13, 0x45800000, v0
	v_cndmask_b32_e32 v0, v0, v13, vcc
	v_mul_f32_e32 v0, v36, v0
	v_pk_mul_f32 v[242:243], v[136:137], v[0:1] op_sel_hi:[1,0]
	v_pk_mul_f32 v[244:245], v[138:139], v[0:1] op_sel_hi:[1,0]
	v_pk_mul_f32 v[246:247], v[140:141], v[0:1] op_sel_hi:[1,0]
	v_pk_mul_f32 v[248:249], v[142:143], v[0:1] op_sel_hi:[1,0]
	v_pk_mul_f32 v[242:243], v[96:97], v[242:243]
	v_pk_mul_f32 v[244:245], v[98:99], v[244:245]
	v_pk_mul_f32 v[246:247], v[100:101], v[246:247]
	v_pk_mul_f32 v[248:249], v[102:103], v[248:249]
	v_cvt_pk_bf16_f32 v250, v242, v243
	v_cvt_pk_bf16_f32 v251, v244, v245
	v_cvt_pk_bf16_f32 v252, v246, v247
	v_cvt_pk_bf16_f32 v253, v248, v249
	global_store_dwordx4 v30, v[250:253], s[8:9]
	s_mov_b64 exec, s[4:5]
	s_and_b32 s22, s48, 0xfff
	v_mov_b32_e32 v2, v104
	v_mov_b32_e32 v3, v105
	v_mov_b32_e32 v4, v106
	v_mov_b32_e32 v5, v107
	v_mov_b32_e32 v6, v108
	v_mov_b32_e32 v7, v109
	v_mov_b32_e32 v8, v110
	v_mov_b32_e32 v9, v111
	s_cmp_lt_u32 s22, 2
	s_cbranch_scc1 .Lrw_t1_1
	v_lshlrev_b32_e32 v136, 16, v164
	v_and_b32_e32 v137, s26, v164
	v_lshlrev_b32_e32 v138, 16, v165
	v_and_b32_e32 v139, s26, v165
	v_lshlrev_b32_e32 v140, 16, v166
	v_and_b32_e32 v141, s26, v166
	v_lshlrev_b32_e32 v142, 16, v167
	v_and_b32_e32 v143, s26, v167
	v_lshlrev_b32_e32 v242, 16, v168
	v_and_b32_e32 v243, s26, v168
	v_lshlrev_b32_e32 v244, 16, v169
	v_and_b32_e32 v245, s26, v169
	v_lshlrev_b32_e32 v246, 16, v170
	v_and_b32_e32 v247, s26, v170
	v_lshlrev_b32_e32 v248, 16, v171
	v_and_b32_e32 v249, s26, v171
	v_pk_mul_f32 v[136:137], v[112:113], v[136:137]
	v_pk_mul_f32 v[138:139], v[114:115], v[138:139]
	v_pk_mul_f32 v[140:141], v[116:117], v[140:141]
	v_pk_mul_f32 v[142:143], v[118:119], v[142:143]
	v_pk_fma_f32 v[2:3], v[136:137], v[242:243], v[2:3]
	v_pk_fma_f32 v[4:5], v[138:139], v[244:245], v[4:5]
	v_pk_fma_f32 v[6:7], v[140:141], v[246:247], v[6:7]
	v_pk_fma_f32 v[8:9], v[142:143], v[248:249], v[8:9]
; __device__ __forceinline__ void phase_B2(CArgs& a, int l, unsigned char* lds, const int tid, const int bx, const int G) {
;     ...
;         {
;             const int h = lane >> 4, e0 = (lane & 15) * 8;
;             const u32x4 w0 = *(const u32x4*)(OR + (size_t)row * 1024 + h * 256 + e0), w1 = *(const u32x4*)(OR + (size_t)row * 1024 + h * 256 + 128 + e0);
;             float v[8] = {bflo(w0.x) - lam * bflo(w1.x), bfhi(w0.x) - lam * bfhi(w1.x), bflo(w0.y) - lam * bflo(w1.y), bfhi(w0.y) - lam * bfhi(w1.y),
;                           bflo(w0.z) - lam * bflo(w1.z), bfhi(w0.z) - lam * bfhi(w1.z), bflo(w0.w) - lam * bflo(w1.w), bfhi(w0.w) - lam * bfhi(w1.w)};
;             float s = 0.f;
; #pragma unroll
;             for (int i = 0; i < 8; ++i) s += v[i] * v[i];
;             s += __shfl_xor(s, 1); s += __shfl_xor(s, 2); s += __shfl_xor(s, 4); s += __shfl_xor(s, 8);
;             const float r = rsqrtf(s * (1.f / 128.f) + EPS) * post; const float* g = a.in[I_SUBLN] + l * 128 + e0;
;     ...
;         if (lane < 32) {
;             const int ch = lane * 8, pos = row & (SEQ - 1);
;             const float* cw = a.in[I_SCW] + l * 3 * 256 + ch; const float* cb = a.in[I_SCB] + l * 256 + ch;
;             float y[8];
; #pragma unroll
;             for (int i = 0; i < 8; ++i) y[i] = cb[i];
; #pragma unroll
;             for (int k = 0; k < 3; ++k) { const int dt = 2 - k; if (pos >= dt) {
;                 const u32x4 cv = *(const u32x4*)(SC + (size_t)(row - dt) * 256 + ch), xv = *(const u32x4*)(SX + (size_t)(row - dt) * 256 + ch); const float* w = cw + k * 256;
;                 y[0] += w[0] * bflo(cv.x) * bflo(xv.x); y[1] += w[1] * bfhi(cv.x) * bfhi(xv.x); y[2] += w[2] * bflo(cv.y) * bflo(xv.y); y[3] += w[3] * bfhi(cv.y) * bfhi(xv.y);
;                 y[4] += w[4] * bflo(cv.z) * bflo(xv.z); y[5] += w[5] * bfhi(cv.z) * bfhi(xv.z); y[6] += w[6] * bflo(cv.w) * bflo(xv.w); y[7] += w[7] * bfhi(cv.w) * bfhi(xv.w); } }
;             const u32x4 bv = *(const u32x4*)(SB + (size_t)row * 256 + ch);
;             u32x4 o; o.x = cvt_pk_bf16(y[0] * bflo(bv.x), y[1] * bfhi(bv.x)); o.y = cvt_pk_bf16(y[2] * bflo(bv.y), y[3] * bfhi(bv.y));
;             o.z = cvt_pk_bf16(y[4] * bflo(bv.z), y[5] * bfhi(bv.z)); o.w = cvt_pk_bf16(y[6] * bflo(bv.w), y[7] * bfhi(bv.w));
;             *(u32x4*)(OC + (size_t)row * 1024 + 768 + ch) = o;
.Lrw_t1_1:
	s_cmp_lt_u32 s22, 1
	s_cbranch_scc1 .Lrw_t0_1
	v_lshlrev_b32_e32 v136, 16, v172
	v_and_b32_e32 v137, s26, v172
	v_lshlrev_b32_e32 v138, 16, v173
	v_and_b32_e32 v139, s26, v173
	v_lshlrev_b32_e32 v140, 16, v174
	v_and_b32_e32 v141, s26, v174
	v_lshlrev_b32_e32 v142, 16, v175
	v_and_b32_e32 v143, s26, v175
	v_lshlrev_b32_e32 v242, 16, v176
	v_and_b32_e32 v243, s26, v176
	v_lshlrev_b32_e32 v244, 16, v177
	v_and_b32_e32 v245, s26, v177
	v_lshlrev_b32_e32 v246, 16, v178
	v_and_b32_e32 v247, s26, v178
	v_lshlrev_b32_e32 v248, 16, v179
	v_and_b32_e32 v249, s26, v179
	v_pk_mul_f32 v[136:137], v[120:121], v[136:137]
	v_pk_mul_f32 v[138:139], v[122:123], v[138:139]
	v_pk_mul_f32 v[140:141], v[124:125], v[140:141]
	v_pk_mul_f32 v[142:143], v[126:127], v[142:143]
	v_pk_fma_f32 v[2:3], v[136:137], v[242:243], v[2:3]
	v_pk_fma_f32 v[4:5], v[138:139], v[244:245], v[4:5]
	v_pk_fma_f32 v[6:7], v[140:141], v[246:247], v[6:7]
	v_pk_fma_f32 v[8:9], v[142:143], v[248:249], v[8:9]
.Lrw_t0_1:
	v_lshlrev_b32_e32 v136, 16, v180
	v_and_b32_e32 v137, s26, v180
	v_lshlrev_b32_e32 v138, 16, v181
	v_and_b32_e32 v139, s26, v181
	v_lshlrev_b32_e32 v140, 16, v182
	v_and_b32_e32 v141, s26, v182
	v_lshlrev_b32_e32 v142, 16, v183
	v_and_b32_e32 v143, s26, v183
	v_lshlrev_b32_e32 v242, 16, v234
	v_and_b32_e32 v243, s26, v234
	v_lshlrev_b32_e32 v244, 16, v235
	v_and_b32_e32 v245, s26, v235
	v_lshlrev_b32_e32 v246, 16, v236
	v_and_b32_e32 v247, s26, v236
	v_lshlrev_b32_e32 v248, 16, v237
	v_and_b32_e32 v249, s26, v237
	v_pk_mul_f32 v[136:137], v[128:129], v[136:137]
	v_pk_mul_f32 v[138:139], v[130:131], v[138:139]
	v_pk_mul_f32 v[140:141], v[132:133], v[140:141]
	v_pk_mul_f32 v[142:143], v[134:135], v[142:143]
	v_pk_fma_f32 v[2:3], v[136:137], v[242:243], v[2:3]
	v_pk_fma_f32 v[4:5], v[138:139], v[244:245], v[4:5]
	v_pk_fma_f32 v[6:7], v[140:141], v[246:247], v[6:7]
	v_pk_fma_f32 v[8:9], v[142:143], v[248:249], v[8:9]
	v_lshlrev_b32_e32 v136, 16, v238
	v_and_b32_e32 v137, s26, v238
	v_lshlrev_b32_e32 v138, 16, v239
	v_and_b32_e32 v139, s26, v239
	v_lshlrev_b32_e32 v140, 16, v240
	v_and_b32_e32 v141, s26, v240
	v_lshlrev_b32_e32 v142, 16, v241
	v_and_b32_e32 v143, s26, v241
	v_pk_mul_f32 v[2:3], v[2:3], v[136:137]
	v_pk_mul_f32 v[4:5], v[4:5], v[138:139]
	v_pk_mul_f32 v[6:7], v[6:7], v[140:141]
	v_pk_mul_f32 v[8:9], v[8:9], v[142:143]
	v_cvt_pk_bf16_f32 v88, v2, v3
	v_cvt_pk_bf16_f32 v89, v4, v5
	v_cvt_pk_bf16_f32 v90, v6, v7
	v_cvt_pk_bf16_f32 v91, v8, v9
	global_store_dwordx4 v28, v[88:91], s[8:9]
	s_mov_b64 exec, s[4:5]
	global_load_dwordx4 v[164:167], v24, s[12:13] offset:-1024
	global_load_dwordx4 v[168:171], v24, s[14:15] offset:-1024
	global_load_dwordx4 v[172:175], v24, s[12:13] offset:-512
	global_load_dwordx4 v[176:179], v24, s[14:15] offset:-512
	global_load_dwordx4 v[180:183], v24, s[12:13]
	global_load_dwordx4 v[234:237], v24, s[14:15]
	global_load_dwordx4 v[238:241], v24, s[10:11]
	s_mov_b64 exec, -1
	global_load_dwordx4 v[156:159], v26, s[18:19]
	global_load_dwordx4 v[160:163], v26, s[18:19] offset:256
	v_add_u32_e32 v24, s50, v24
	v_add_u32_e32 v26, s51, v26
	v_add_u32_e32 v30, s51, v30
	v_add_u32_e32 v28, s51, v28
	s_add_i32 s48, s48, s49
.Lrw_body2:
	s_cmp_ge_u32 s48, s27
	s_cbranch_scc1 .Lrw_exit
	s_waitcnt vmcnt(22)
	v_lshlrev_b32_e32 v136, 16, v40
	v_and_b32_e32 v137, s26, v40
	v_lshlrev_b32_e32 v138, 16, v41
	v_and_b32_e32 v139, s26, v41
	v_lshlrev_b32_e32 v140, 16, v42
	v_and_b32_e32 v141, s26, v42
	v_lshlrev_b32_e32 v142, 16, v43
	v_and_b32_e32 v143, s26, v43
	v_lshlrev_b32_e32 v242, 16, v44
	v_and_b32_e32 v243, s26, v44
	v_lshlrev_b32_e32 v244, 16, v45
	v_and_b32_e32 v245, s26, v45
	v_lshlrev_b32_e32 v246, 16, v46
	v_and_b32_e32 v247, s26, v46
	v_lshlrev_b32_e32 v248, 16, v47
	v_and_b32_e32 v249, s26, v47
	v_pk_fma_f32 v[136:137], v[10:11], v[242:243], v[136:137] neg_lo:[1,0,0] neg_hi:[1,0,0]
	v_pk_fma_f32 v[138:139], v[10:11], v[244:245], v[138:139] neg_lo:[1,0,0] neg_hi:[1,0,0]
	v_pk_fma_f32 v[140:141], v[10:11], v[246:247], v[140:141] neg_lo:[1,0,0] neg_hi:[1,0,0]
	v_pk_fma_f32 v[142:143], v[10:11], v[248:249], v[142:143] neg_lo:[1,0,0] neg_hi:[1,0,0]
	v_mul_f32_e32 v0, v137, v137
	v_pk_mul_f32 v[244:245], v[138:139], v[138:139]
	v_pk_mul_f32 v[246:247], v[140:141], v[140:141]
	v_pk_mul_f32 v[248:249], v[142:143], v[142:143]
	v_fmac_f32_e32 v0, v136, v136
	v_add_f32_e32 v0, v244, v0
	v_add_f32_e32 v0, v245, v0
	v_add_f32_e32 v0, v246, v0
	v_add_f32_e32 v0, v247, v0
	v_add_f32_e32 v0, v248, v0
	v_add_f32_e32 v0, v249, v0
	s_nop 1
	v_add_f32_dpp v0, v0, v0 quad_perm:[1,0,3,2] row_mask:0xf bank_mask:0xf
	s_nop 1
	v_add_f32_dpp v0, v0, v0 quad_perm:[2,3,0,1] row_mask:0xf bank_mask:0xf
	s_nop 1
	v_add_f32_dpp v0, v0, v0 row_half_mirror row_mask:0xf bank_mask:0xf
	s_nop 1
	v_add_f32_dpp v0, v0, v0 row_mirror row_mask:0xf bank_mask:0xf
	s_nop 0
	v_fmamk_f32 v0, v0, 0x3c000000, v184
	v_mul_f32_e32 v13, 0x4b800000, v0
	v_cmp_gt_f32_e32 vcc, s74, v0
	s_nop 1
	v_cndmask_b32_e32 v0, v0, v13, vcc
	v_rsq_f32_e32 v0, v0
	s_nop 0
	v_mul_f32_e32 v13, 0x45800000, v0
	v_cndmask_b32_e32 v0, v0, v13, vcc
	v_mul_f32_e32 v0, v36, v0
	v_pk_mul_f32 v[242:243], v[136:137], v[0:1] op_sel_hi:[1,0]
	v_pk_mul_f32 v[244:245], v[138:139], v[0:1] op_sel_hi:[1,0]
	v_pk_mul_f32 v[246:247], v[140:141], v[0:1] op_sel_hi:[1,0]
	v_pk_mul_f32 v[248:249], v[142:143], v[0:1] op_sel_hi:[1,0]
	v_pk_mul_f32 v[242:243], v[96:97], v[242:243]
	v_pk_mul_f32 v[244:245], v[98:99], v[244:245]
	v_pk_mul_f32 v[246:247], v[100:101], v[246:247]
	v_pk_mul_f32 v[248:249], v[102:103], v[248:249]
	v_cvt_pk_bf16_f32 v250, v242, v243
	v_cvt_pk_bf16_f32 v251, v244, v245
	v_cvt_pk_bf16_f32 v252, v246, v247
	v_cvt_pk_bf16_f32 v253, v248, v249
	global_store_dwordx4 v30, v[250:253], s[8:9]
	s_mov_b64 exec, s[4:5]
	s_and_b32 s22, s48, 0xfff
	v_mov_b32_e32 v2, v104
	v_mov_b32_e32 v3, v105
	v_mov_b32_e32 v4, v106
	v_mov_b32_e32 v5, v107
	v_mov_b32_e32 v6, v108
	v_mov_b32_e32 v7, v109
	v_mov_b32_e32 v8, v110
	v_mov_b32_e32 v9, v111
	s_cmp_lt_u32 s22, 2
	s_cbranch_scc1 .Lrw_t1_2
	v_lshlrev_b32_e32 v136, 16, v48
	v_and_b32_e32 v137, s26, v48
	v_lshlrev_b32_e32 v138, 16, v49
	v_and_b32_e32 v139, s26, v49
	v_lshlrev_b32_e32 v140, 16, v50
	v_and_b32_e32 v141, s26, v50
	v_lshlrev_b32_e32 v142, 16, v51
	v_and_b32_e32 v143, s26, v51
	v_lshlrev_b32_e32 v242, 16, v52
	v_and_b32_e32 v243, s26, v52
	v_lshlrev_b32_e32 v244, 16, v53
	v_and_b32_e32 v245, s26, v53
	v_lshlrev_b32_e32 v246, 16, v54
	v_and_b32_e32 v247, s26, v54
	v_lshlrev_b32_e32 v248, 16, v55
	v_and_b32_e32 v249, s26, v55
	v_pk_mul_f32 v[136:137], v[112:113], v[136:137]
	v_pk_mul_f32 v[138:139], v[114:115], v[138:139]
	v_pk_mul_f32 v[140:141], v[116:117], v[140:141]
	v_pk_mul_f32 v[142:143], v[118:119], v[142:143]
	v_pk_fma_f32 v[2:3], v[136:137], v[242:243], v[2:3]
	v_pk_fma_f32 v[4:5], v[138:139], v[244:245], v[4:5]
	v_pk_fma_f32 v[6:7], v[140:141], v[246:247], v[6:7]
	v_pk_fma_f32 v[8:9], v[142:143], v[248:249], v[8:9]
; __device__ __forceinline__ unsigned cvt_pk_bf16(float lo, float hi) { unsigned r; asm volatile("v_cvt_pk_bf16_f32 %0, %1, %2" : "=v"(r) : "v"(lo), "v"(hi)); return r; }
; __device__ __forceinline__ float bflo(unsigned w) { return __uint_as_float(w << 16); }
; __device__ __forceinline__ float bfhi(unsigned w) { return __uint_as_float(w & 0xffff0000u); }
; __device__ __forceinline__ void phase_B2(CArgs& a, int l, unsigned char* lds, const int tid, const int bx, const int G) {
;     ...
;         if (lane < 32) {
;             const int ch = lane * 8, pos = row & (SEQ - 1);
;             const float* cw = a.in[I_SCW] + l * 3 * 256 + ch; const float* cb = a.in[I_SCB] + l * 256 + ch;
;             float y[8];
; #pragma unroll
;             for (int i = 0; i < 8; ++i) y[i] = cb[i];
; #pragma unroll
;             for (int k = 0; k < 3; ++k) { const int dt = 2 - k; if (pos >= dt) {
;                 const u32x4 cv = *(const u32x4*)(SC + (size_t)(row - dt) * 256 + ch), xv = *(const u32x4*)(SX + (size_t)(row - dt) * 256 + ch); const float* w = cw + k * 256;
;                 y[0] += w[0] * bflo(cv.x) * bflo(xv.x); y[1] += w[1] * bfhi(cv.x) * bfhi(xv.x); y[2] += w[2] * bflo(cv.y) * bflo(xv.y); y[3] += w[3] * bfhi(cv.y) * bfhi(xv.y);
;                 y[4] += w[4] * bflo(cv.z) * bflo(xv.z); y[5] += w[5] * bfhi(cv.z) * bfhi(xv.z); y[6] += w[6] * bflo(cv.w) * bflo(xv.w); y[7] += w[7] * bfhi(cv.w) * bfhi(xv.w); } }
;             const u32x4 bv = *(const u32x4*)(SB + (size_t)row * 256 + ch);
;             u32x4 o; o.x = cvt_pk_bf16(y[0] * bflo(bv.x), y[1] * bfhi(bv.x)); o.y = cvt_pk_bf16(y[2] * bflo(bv.y), y[3] * bfhi(bv.y));
;             o.z = cvt_pk_bf16(y[4] * bflo(bv.z), y[5] * bfhi(bv.z)); o.w = cvt_pk_bf16(y[6] * bflo(bv.w), y[7] * bfhi(bv.w));
;             *(u32x4*)(OC + (size_t)row * 1024 + 768 + ch) = o;
.Lrw_t1_2:
	s_cmp_lt_u32 s22, 1
	s_cbranch_scc1 .Lrw_t0_2
	v_lshlrev_b32_e32 v136, 16, v56
	v_and_b32_e32 v137, s26, v56
	v_lshlrev_b32_e32 v138, 16, v57
	v_and_b32_e32 v139, s26, v57
	v_lshlrev_b32_e32 v140, 16, v58
	v_and_b32_e32 v141, s26, v58
	v_lshlrev_b32_e32 v142, 16, v59
	v_and_b32_e32 v143, s26, v59
	v_lshlrev_b32_e32 v242, 16, v60
	v_and_b32_e32 v243, s26, v60
	v_lshlrev_b32_e32 v244, 16, v61
	v_and_b32_e32 v245, s26, v61
	v_lshlrev_b32_e32 v246, 16, v62
	v_and_b32_e32 v247, s26, v62
	v_lshlrev_b32_e32 v248, 16, v63
	v_and_b32_e32 v249, s26, v63
	v_pk_mul_f32 v[136:137], v[120:121], v[136:137]
	v_pk_mul_f32 v[138:139], v[122:123], v[138:139]
	v_pk_mul_f32 v[140:141], v[124:125], v[140:141]
	v_pk_mul_f32 v[142:143], v[126:127], v[142:143]
	v_pk_fma_f32 v[2:3], v[136:137], v[242:243], v[2:3]
	v_pk_fma_f32 v[4:5], v[138:139], v[244:245], v[4:5]
	v_pk_fma_f32 v[6:7], v[140:141], v[246:247], v[6:7]
	v_pk_fma_f32 v[8:9], v[142:143], v[248:249], v[8:9]
.Lrw_t0_2:
	v_lshlrev_b32_e32 v136, 16, v76
	v_and_b32_e32 v137, s26, v76
	v_lshlrev_b32_e32 v138, 16, v77
	v_and_b32_e32 v139, s26, v77
	v_lshlrev_b32_e32 v140, 16, v78
	v_and_b32_e32 v141, s26, v78
	v_lshlrev_b32_e32 v142, 16, v79
	v_and_b32_e32 v143, s26, v79
	v_lshlrev_b32_e32 v242, 16, v80
	v_and_b32_e32 v243, s26, v80
	v_lshlrev_b32_e32 v244, 16, v81
	v_and_b32_e32 v245, s26, v81
	v_lshlrev_b32_e32 v246, 16, v82
	v_and_b32_e32 v247, s26, v82
	v_lshlrev_b32_e32 v248, 16, v83
	v_and_b32_e32 v249, s26, v83
	v_pk_mul_f32 v[136:137], v[128:129], v[136:137]
	v_pk_mul_f32 v[138:139], v[130:131], v[138:139]
	v_pk_mul_f32 v[140:141], v[132:133], v[140:141]
	v_pk_mul_f32 v[142:143], v[134:135], v[142:143]
	v_pk_fma_f32 v[2:3], v[136:137], v[242:243], v[2:3]
	v_pk_fma_f32 v[4:5], v[138:139], v[244:245], v[4:5]
	v_pk_fma_f32 v[6:7], v[140:141], v[246:247], v[6:7]
	v_pk_fma_f32 v[8:9], v[142:143], v[248:249], v[8:9]
	v_lshlrev_b32_e32 v136, 16, v84
	v_and_b32_e32 v137, s26, v84
	v_lshlrev_b32_e32 v138, 16, v85
	v_and_b32_e32 v139, s26, v85
	v_lshlrev_b32_e32 v140, 16, v86
	v_and_b32_e32 v141, s26, v86
	v_lshlrev_b32_e32 v142, 16, v87
	v_and_b32_e32 v143, s26, v87
	v_pk_mul_f32 v[2:3], v[2:3], v[136:137]
	v_pk_mul_f32 v[4:5], v[4:5], v[138:139]
	v_pk_mul_f32 v[6:7], v[6:7], v[140:141]
	v_pk_mul_f32 v[8:9], v[8:9], v[142:143]
	v_cvt_pk_bf16_f32 v88, v2, v3
	v_cvt_pk_bf16_f32 v89, v4, v5
	v_cvt_pk_bf16_f32 v90, v6, v7
	v_cvt_pk_bf16_f32 v91, v8, v9
	global_store_dwordx4 v28, v[88:91], s[8:9]
	s_mov_b64 exec, s[4:5]
	global_load_dwordx4 v[48:51], v24, s[12:13] offset:-1024
	global_load_dwordx4 v[52:55], v24, s[14:15] offset:-1024
	global_load_dwordx4 v[56:59], v24, s[12:13] offset:-512
	global_load_dwordx4 v[60:63], v24, s[14:15] offset:-512
	global_load_dwordx4 v[76:79], v24, s[12:13]
	global_load_dwordx4 v[80:83], v24, s[14:15]
	global_load_dwordx4 v[84:87], v24, s[10:11]
	s_mov_b64 exec, -1
	global_load_dwordx4 v[40:43], v26, s[18:19]
	global_load_dwordx4 v[44:47], v26, s[18:19] offset:256
	v_add_u32_e32 v24, s50, v24
	v_add_u32_e32 v26, s51, v26
	v_add_u32_e32 v30, s51, v30
	v_add_u32_e32 v28, s51, v28
	s_add_i32 s48, s48, s49
	s_branch .Lrw_body0
.Lrw_exit:
	s_mov_b64 exec, -1
	s_waitcnt vmcnt(0)
